# v65 + up GEMM: epilogue row group 0 math (final ai=0 accumulators) hoisted into the last compute segment of the K loop, interleaved between its MFMAs with temporaries renamed to dead DMA address regis
# baseline (speedup 1.0000x reference)
.LBB0_180:
	s_add_u32 s62, s60, 0xfffc0080
	s_addc_u32 s63, s61, -1
	s_add_i32 s86, 0, 0x10000
	s_cmp_eq_u32 s85, 12
	s_cselect_b32 vcc_hi, s47, s63
	s_cselect_b32 vcc_lo, s82, s62
	v_add_u32_e32 v142, s86, v145
	s_cselect_b32 s63, s21, s84
	s_cselect_b32 s62, s83, s89
	s_add_i32 s92, 0, 0x14000
	ds_read_b128 v[138:141], v142
	ds_read_b128 v[172:175], v142 offset:1024
	ds_read_b128 v[176:179], v142 offset:2048
	ds_read_b128 v[180:183], v142 offset:3072
	v_add_u32_e32 v142, s92, v145
	ds_read_b128 v[184:187], v142
	ds_read_b128 v[188:191], v142 offset:1024
	ds_read_b128 v[192:195], v142 offset:2048
	ds_read_b128 v[196:199], v142 offset:3072
	v_lshl_add_u64 v[142:143], s[60:61], 0, v[136:137]
	s_add_i32 m0, s68, 0xc000
	ds_read_b128 v[210:213], v148
	ds_read_b128 v[214:217], v148 offset:1024
	ds_read_b128 v[218:221], v148 offset:2048
	ds_read_b128 v[224:227], v148 offset:3072
	ds_read_b128 v[228:231], v148 offset:4096
	ds_read_b128 v[232:235], v148 offset:5120
	ds_read_b128 v[236:239], v148 offset:6144
	ds_read_b128 v[240:243], v148 offset:7168
	global_load_lds_dwordx4 v[142:143], off
	v_lshl_add_u64 v[142:143], s[60:61], 0, v[134:135]
	s_add_i32 m0, s68, 0xe000
	s_nop 0
	global_load_lds_dwordx4 v[142:143], off
	s_waitcnt vmcnt(8)
	s_waitcnt lgkmcnt(0)
	s_barrier
	s_setprio 1
	s_waitcnt lgkmcnt(0)
	v_mfma_f32_16x16x32_bf16 v[124:127], v[138:141], v[210:213], v[124:127]
	v_mfma_f32_16x16x32_bf16 v[116:119], v[176:179], v[210:213], v[116:119]
	v_mfma_f32_16x16x32_bf16 v[108:111], v[138:141], v[218:221], v[108:111]
	v_mfma_f32_16x16x32_bf16 v[100:103], v[176:179], v[218:221], v[100:103]
	v_mfma_f32_16x16x32_bf16 v[92:95], v[138:141], v[228:231], v[92:95]
	v_mfma_f32_16x16x32_bf16 v[84:87], v[176:179], v[228:231], v[84:87]
	v_mfma_f32_16x16x32_bf16 v[76:79], v[138:141], v[236:239], v[76:79]
	v_mfma_f32_16x16x32_bf16 v[68:71], v[176:179], v[236:239], v[68:71]
	v_mfma_f32_16x16x32_bf16 v[124:127], v[172:175], v[214:217], v[124:127]
	v_mfma_f32_16x16x32_bf16 v[116:119], v[180:183], v[214:217], v[116:119]
	v_mfma_f32_16x16x32_bf16 v[108:111], v[172:175], v[224:227], v[108:111]
	v_mfma_f32_16x16x32_bf16 v[100:103], v[180:183], v[224:227], v[100:103]
	v_mfma_f32_16x16x32_bf16 v[92:95], v[172:175], v[232:235], v[92:95]
	v_mfma_f32_16x16x32_bf16 v[84:87], v[180:183], v[232:235], v[84:87]
	v_mfma_f32_16x16x32_bf16 v[76:79], v[172:175], v[240:243], v[76:79]
	v_mfma_f32_16x16x32_bf16 v[68:71], v[180:183], v[240:243], v[68:71]
	s_setprio 0
	s_setprio 1
	v_mfma_f32_16x16x32_bf16 v[120:123], v[184:187], v[210:213], v[120:123]
	v_mfma_f32_16x16x32_bf16 v[112:115], v[192:195], v[210:213], v[112:115]
	v_mfma_f32_16x16x32_bf16 v[104:107], v[184:187], v[218:221], v[104:107]
	v_mfma_f32_16x16x32_bf16 v[96:99], v[192:195], v[218:221], v[96:99]
	v_mfma_f32_16x16x32_bf16 v[88:91], v[184:187], v[228:231], v[88:91]
	v_mfma_f32_16x16x32_bf16 v[80:83], v[192:195], v[228:231], v[80:83]
	v_mfma_f32_16x16x32_bf16 v[72:75], v[184:187], v[236:239], v[72:75]
	v_mfma_f32_16x16x32_bf16 v[64:67], v[192:195], v[236:239], v[64:67]
	v_mfma_f32_16x16x32_bf16 v[120:123], v[188:191], v[214:217], v[120:123]
	v_mfma_f32_16x16x32_bf16 v[112:115], v[196:199], v[214:217], v[112:115]
	v_mfma_f32_16x16x32_bf16 v[104:107], v[188:191], v[224:227], v[104:107]
	v_mfma_f32_16x16x32_bf16 v[96:99], v[196:199], v[224:227], v[96:99]
	v_mfma_f32_16x16x32_bf16 v[88:91], v[188:191], v[232:235], v[88:91]
	v_mfma_f32_16x16x32_bf16 v[80:83], v[196:199], v[232:235], v[80:83]
	v_mfma_f32_16x16x32_bf16 v[72:75], v[188:191], v[240:243], v[72:75]
	v_mfma_f32_16x16x32_bf16 v[64:67], v[196:199], v[240:243], v[64:67]
	s_setprio 0
	s_barrier
	s_add_i32 s86, s86, s67
	v_lshl_add_u64 v[142:143], s[62:63], 0, v[152:153]
	s_mov_b32 m0, s86
	ds_read_b128 v[210:213], v148 offset:16384
	ds_read_b128 v[214:217], v148 offset:17408
	ds_read_b128 v[218:221], v148 offset:18432
	ds_read_b128 v[224:227], v148 offset:19456
	ds_read_b128 v[228:231], v148 offset:20480
	ds_read_b128 v[232:235], v148 offset:21504
	ds_read_b128 v[236:239], v148 offset:22528
	ds_read_b128 v[240:243], v148 offset:23552
	global_load_lds_dwordx4 v[142:143], off
	s_add_i32 m0, s86, 0x2000
	s_add_u32 s86, s62, 0x40000
	v_lshl_add_u64 v[150:151], s[62:63], 0, v[128:129]
	s_addc_u32 s87, s63, 0
	s_add_i32 s92, s92, s67
	global_load_lds_dwordx4 v[150:151], off
	v_lshl_add_u64 v[244:245], s[86:87], 0, v[152:153]
	s_mov_b32 m0, s92
	v_lshl_add_u64 v[246:247], vcc, 0, v[130:131]
	global_load_lds_dwordx4 v[244:245], off
	v_lshl_add_u64 v[244:245], s[86:87], 0, v[128:129]
	s_add_i32 m0, s92, 0x2000
	s_nop 0
	global_load_lds_dwordx4 v[244:245], off
	v_lshl_add_u64 v[244:245], vcc, 0, v[132:133]
	s_mov_b32 m0, s68
	s_nop 0
	global_load_lds_dwordx4 v[244:245], off
	s_mov_b32 m0, s69
	s_nop 0
	global_load_lds_dwordx4 v[246:247], off
	s_waitcnt vmcnt(8)
	s_waitcnt lgkmcnt(0)
	s_barrier
	s_setprio 1
	s_waitcnt lgkmcnt(0)
	v_mfma_f32_16x16x32_bf16 v[60:63], v[138:141], v[210:213], v[60:63]
	v_mfma_f32_16x16x32_bf16 v[52:55], v[176:179], v[210:213], v[52:55]
	v_mfma_f32_16x16x32_bf16 v[44:47], v[138:141], v[218:221], v[44:47]
	v_mfma_f32_16x16x32_bf16 v[36:39], v[176:179], v[218:221], v[36:39]
	v_mfma_f32_16x16x32_bf16 v[28:31], v[138:141], v[228:231], v[28:31]
	v_mfma_f32_16x16x32_bf16 v[20:23], v[176:179], v[228:231], v[20:23]
	v_mfma_f32_16x16x32_bf16 v[12:15], v[138:141], v[236:239], v[12:15]
	v_mfma_f32_16x16x32_bf16 v[4:7], v[176:179], v[236:239], v[4:7]
	v_mfma_f32_16x16x32_bf16 v[60:63], v[172:175], v[214:217], v[60:63]
	v_mfma_f32_16x16x32_bf16 v[52:55], v[180:183], v[214:217], v[52:55]
	v_mfma_f32_16x16x32_bf16 v[44:47], v[172:175], v[224:227], v[44:47]
	v_mfma_f32_16x16x32_bf16 v[36:39], v[180:183], v[224:227], v[36:39]
	v_mfma_f32_16x16x32_bf16 v[28:31], v[172:175], v[232:235], v[28:31]
	v_mfma_f32_16x16x32_bf16 v[20:23], v[180:183], v[232:235], v[20:23]
	v_mfma_f32_16x16x32_bf16 v[12:15], v[172:175], v[240:243], v[12:15]
	v_mfma_f32_16x16x32_bf16 v[4:7], v[180:183], v[240:243], v[4:7]
	s_setprio 0
	s_setprio 1
	v_mfma_f32_16x16x32_bf16 v[56:59], v[184:187], v[210:213], v[56:59]
	v_mfma_f32_16x16x32_bf16 v[48:51], v[192:195], v[210:213], v[48:51]
	v_mfma_f32_16x16x32_bf16 v[40:43], v[184:187], v[218:221], v[40:43]
	v_mfma_f32_16x16x32_bf16 v[32:35], v[192:195], v[218:221], v[32:35]
	v_mfma_f32_16x16x32_bf16 v[24:27], v[184:187], v[228:231], v[24:27]
	v_mfma_f32_16x16x32_bf16 v[16:19], v[192:195], v[228:231], v[16:19]
	v_mfma_f32_16x16x32_bf16 v[8:11], v[184:187], v[236:239], v[8:11]
	v_mfma_f32_16x16x32_bf16 v[0:3], v[192:195], v[236:239], v[0:3]
	v_mfma_f32_16x16x32_bf16 v[56:59], v[188:191], v[214:217], v[56:59]
	v_mfma_f32_16x16x32_bf16 v[48:51], v[196:199], v[214:217], v[48:51]
	v_mfma_f32_16x16x32_bf16 v[40:43], v[188:191], v[224:227], v[40:43]
	v_mfma_f32_16x16x32_bf16 v[32:35], v[196:199], v[224:227], v[32:35]
	v_mfma_f32_16x16x32_bf16 v[24:27], v[188:191], v[232:235], v[24:27]
	v_mfma_f32_16x16x32_bf16 v[16:19], v[196:199], v[232:235], v[16:19]
	v_mfma_f32_16x16x32_bf16 v[8:11], v[188:191], v[240:243], v[8:11]
	v_mfma_f32_16x16x32_bf16 v[0:3], v[196:199], v[240:243], v[0:3]
	s_setprio 0
	s_barrier
	s_add_i32 s92, 0, 0x18000
	v_add_u32_e32 v149, s92, v145
	s_add_i32 s93, 0, 0x1c000
	ds_read_b128 v[138:141], v149
	ds_read_b128 v[172:175], v149 offset:1024
	ds_read_b128 v[176:179], v149 offset:2048
	ds_read_b128 v[180:183], v149 offset:3072
	v_add_u32_e32 v149, s93, v145
	ds_read_b128 v[184:187], v149
	ds_read_b128 v[188:191], v149 offset:1024
	ds_read_b128 v[192:195], v149 offset:2048
	ds_read_b128 v[196:199], v149 offset:3072
	s_add_u32 s86, vcc_lo, 0x40000
	s_addc_u32 s87, vcc_hi, 0
	s_mov_b32 m0, s74
	v_lshl_add_u64 v[248:249], s[86:87], 0, v[132:133]
	ds_read_b128 v[210:213], v148 offset:32768
	ds_read_b128 v[214:217], v148 offset:33792
	ds_read_b128 v[218:221], v148 offset:34816
	ds_read_b128 v[224:227], v148 offset:35840
	ds_read_b128 v[228:231], v148 offset:36864
	ds_read_b128 v[232:235], v148 offset:37888
	ds_read_b128 v[236:239], v148 offset:38912
	ds_read_b128 v[240:243], v148 offset:39936
	global_load_lds_dwordx4 v[248:249], off
	v_lshl_add_u64 v[248:249], s[86:87], 0, v[130:131]
	s_mov_b32 m0, s75
	s_nop 0
	global_load_lds_dwordx4 v[248:249], off
	s_waitcnt vmcnt(8)
	s_waitcnt lgkmcnt(0)
	s_barrier
	s_setprio 1
	s_waitcnt lgkmcnt(0)
	v_mfma_f32_16x16x32_bf16 v[124:127], v[138:141], v[210:213], v[124:127]
	v_mfma_f32_16x16x32_bf16 v[116:119], v[176:179], v[210:213], v[116:119]
	v_mfma_f32_16x16x32_bf16 v[108:111], v[138:141], v[218:221], v[108:111]
	v_mfma_f32_16x16x32_bf16 v[100:103], v[176:179], v[218:221], v[100:103]
	v_mfma_f32_16x16x32_bf16 v[92:95], v[138:141], v[228:231], v[92:95]
	v_mfma_f32_16x16x32_bf16 v[84:87], v[176:179], v[228:231], v[84:87]
	v_mfma_f32_16x16x32_bf16 v[76:79], v[138:141], v[236:239], v[76:79]
	v_mfma_f32_16x16x32_bf16 v[68:71], v[176:179], v[236:239], v[68:71]
	v_mfma_f32_16x16x32_bf16 v[124:127], v[172:175], v[214:217], v[124:127]
	v_mfma_f32_16x16x32_bf16 v[116:119], v[180:183], v[214:217], v[116:119]
	v_mfma_f32_16x16x32_bf16 v[108:111], v[172:175], v[224:227], v[108:111]
	v_mfma_f32_16x16x32_bf16 v[100:103], v[180:183], v[224:227], v[100:103]
	v_mfma_f32_16x16x32_bf16 v[92:95], v[172:175], v[232:235], v[92:95]
	v_mfma_f32_16x16x32_bf16 v[84:87], v[180:183], v[232:235], v[84:87]
	v_mfma_f32_16x16x32_bf16 v[76:79], v[172:175], v[240:243], v[76:79]
	v_mfma_f32_16x16x32_bf16 v[68:71], v[180:183], v[240:243], v[68:71]
	s_setprio 0
	s_setprio 1
	v_mfma_f32_16x16x32_bf16 v[120:123], v[184:187], v[210:213], v[120:123]
	v_mfma_f32_16x16x32_bf16 v[112:115], v[192:195], v[210:213], v[112:115]
	v_mfma_f32_16x16x32_bf16 v[104:107], v[184:187], v[218:221], v[104:107]
	v_mfma_f32_16x16x32_bf16 v[96:99], v[192:195], v[218:221], v[96:99]
	v_mfma_f32_16x16x32_bf16 v[88:91], v[184:187], v[228:231], v[88:91]
	v_mfma_f32_16x16x32_bf16 v[80:83], v[192:195], v[228:231], v[80:83]
	v_mfma_f32_16x16x32_bf16 v[72:75], v[184:187], v[236:239], v[72:75]
	v_mfma_f32_16x16x32_bf16 v[64:67], v[192:195], v[236:239], v[64:67]
	v_mfma_f32_16x16x32_bf16 v[120:123], v[188:191], v[214:217], v[120:123]
	v_mfma_f32_16x16x32_bf16 v[112:115], v[196:199], v[214:217], v[112:115]
	v_mfma_f32_16x16x32_bf16 v[104:107], v[188:191], v[224:227], v[104:107]
	v_mfma_f32_16x16x32_bf16 v[96:99], v[196:199], v[224:227], v[96:99]
	v_mfma_f32_16x16x32_bf16 v[88:91], v[188:191], v[232:235], v[88:91]
	v_mfma_f32_16x16x32_bf16 v[80:83], v[196:199], v[232:235], v[80:83]
	v_mfma_f32_16x16x32_bf16 v[72:75], v[188:191], v[240:243], v[72:75]
	v_mfma_f32_16x16x32_bf16 v[64:67], v[196:199], v[240:243], v[64:67]
	s_setprio 0
	s_barrier
	s_add_i32 s86, s92, s67
	v_lshl_add_u64 v[142:143], v[142:143], 0, s[22:23]
	s_mov_b32 m0, s86
	ds_read_b128 v[210:213], v148 offset:49152
	ds_read_b128 v[214:217], v148 offset:50176
	ds_read_b128 v[218:221], v148 offset:51200
	ds_read_b128 v[224:227], v148 offset:52224
	ds_read_b128 v[228:231], v148 offset:53248
	ds_read_b128 v[232:235], v148 offset:54272
	ds_read_b128 v[236:239], v148 offset:55296
	ds_read_b128 v[240:243], v148 offset:56320
	global_load_lds_dwordx4 v[142:143], off
	s_add_i32 m0, s86, 0x2000
	s_add_u32 s62, s62, 0x40080
	v_lshl_add_u64 v[142:143], v[150:151], 0, s[22:23]
	s_addc_u32 s63, s63, 0
	s_add_i32 s86, s93, s67
	global_load_lds_dwordx4 v[142:143], off
	v_lshl_add_u64 v[142:143], s[62:63], 0, v[152:153]
	s_mov_b32 m0, s86
	s_nop 0
	global_load_lds_dwordx4 v[142:143], off
	v_lshl_add_u64 v[142:143], s[62:63], 0, v[128:129]
	s_add_i32 m0, s86, 0x2000
	s_nop 0
	global_load_lds_dwordx4 v[142:143], off
	v_lshl_add_u64 v[142:143], v[244:245], 0, s[22:23]
	s_mov_b32 m0, s77
	s_nop 0
	global_load_lds_dwordx4 v[142:143], off
	v_lshl_add_u64 v[142:143], v[246:247], 0, s[22:23]
	s_mov_b32 m0, s78
	s_nop 0
	global_load_lds_dwordx4 v[142:143], off
	s_waitcnt vmcnt(8)
	s_waitcnt lgkmcnt(0)
	s_cmp_eq_u32 s85, 12
	s_cbranch_scc0 .Lmy_up_lastn
	v_mov_b32_e32 v142, s81
	v_lshlrev_b32_e32 v142, 7, v142
	v_and_b32_e32 v142, 0xc00, v142
	v_add_u32_e32 v142, v142, v146
	ds_read_b32 v150, v142
	s_barrier
	s_setprio 1
	s_waitcnt lgkmcnt(0)
	v_mfma_f32_16x16x32_bf16 v[60:63], v[138:141], v[210:213], v[60:63]
	v_pk_mul_f32 v[120:121], v[124:125], v[120:121]
	v_mul_f32_e32 v142, 0xbfb8aa3b, v150
	v_mfma_f32_16x16x32_bf16 v[52:55], v[176:179], v[210:213], v[52:55]
	v_pk_mul_f32 v[244:245], v[126:127], v[142:143] op_sel_hi:[1,0]
	v_pk_mul_f32 v[246:247], v[124:125], v[142:143] op_sel_hi:[1,0]
	v_mfma_f32_16x16x32_bf16 v[44:47], v[138:141], v[218:221], v[44:47]
	v_exp_f32_e32 v244, v244
	v_exp_f32_e32 v245, v245
	v_mfma_f32_16x16x32_bf16 v[36:39], v[176:179], v[218:221], v[36:39]
	v_exp_f32_e32 v246, v246
	v_exp_f32_e32 v247, v247
	v_mfma_f32_16x16x32_bf16 v[28:31], v[138:141], v[228:231], v[28:31]
	v_mul_f32_e32 v150, v150, v150
	v_pk_add_f32 v[244:245], v[244:245], 1.0 op_sel_hi:[1,0]
	v_mfma_f32_16x16x32_bf16 v[20:23], v[176:179], v[228:231], v[20:23]
	v_pk_mul_f32 v[122:123], v[126:127], v[122:123]
	v_rcp_f32_e32 v244, v244
	v_mfma_f32_16x16x32_bf16 v[12:15], v[138:141], v[236:239], v[12:15]
	v_rcp_f32_e32 v245, v245
	v_pk_add_f32 v[246:247], v[246:247], 1.0 op_sel_hi:[1,0]
	v_mfma_f32_16x16x32_bf16 v[4:7], v[176:179], v[236:239], v[4:7]
	v_rcp_f32_e32 v246, v246
	v_pk_mul_f32 v[124:125], v[150:151], v[244:245] op_sel_hi:[0,1]
	v_mfma_f32_16x16x32_bf16 v[60:63], v[172:175], v[214:217], v[60:63]
	v_pk_mul_f32 v[244:245], v[118:119], v[142:143] op_sel_hi:[1,0]
	v_rcp_f32_e32 v247, v247
	v_mfma_f32_16x16x32_bf16 v[52:55], v[180:183], v[214:217], v[52:55]
	v_pk_mul_f32 v[142:143], v[116:117], v[142:143] op_sel_hi:[1,0]
	v_exp_f32_e32 v244, v244
	v_mfma_f32_16x16x32_bf16 v[44:47], v[172:175], v[224:227], v[44:47]
	v_exp_f32_e32 v245, v245
	v_mfma_f32_16x16x32_bf16 v[36:39], v[180:183], v[224:227], v[36:39]
	v_exp_f32_e32 v142, v142
	v_mfma_f32_16x16x32_bf16 v[28:31], v[172:175], v[232:235], v[28:31]
	v_exp_f32_e32 v143, v143
	v_mfma_f32_16x16x32_bf16 v[20:23], v[180:183], v[232:235], v[20:23]
	v_pk_mul_f32 v[126:127], v[150:151], v[246:247] op_sel_hi:[0,1]
	v_mfma_f32_16x16x32_bf16 v[12:15], v[172:175], v[240:243], v[12:15]
	v_pk_mul_f32 v[122:123], v[122:123], v[124:125]
	v_mfma_f32_16x16x32_bf16 v[4:7], v[180:183], v[240:243], v[4:7]
	v_pk_add_f32 v[124:125], v[244:245], 1.0 op_sel_hi:[1,0]
	s_setprio 0
	s_setprio 1
	v_mfma_f32_16x16x32_bf16 v[56:59], v[184:187], v[210:213], v[56:59]
	v_pk_mul_f32 v[120:121], v[120:121], v[126:127]
	v_mfma_f32_16x16x32_bf16 v[48:51], v[192:195], v[210:213], v[48:51]
	v_pk_add_f32 v[126:127], v[142:143], 1.0 op_sel_hi:[1,0]
	v_mfma_f32_16x16x32_bf16 v[40:43], v[184:187], v[218:221], v[40:43]
	v_rcp_f32_e32 v124, v124
	v_mfma_f32_16x16x32_bf16 v[32:35], v[192:195], v[218:221], v[32:35]
	v_rcp_f32_e32 v125, v125
	v_mfma_f32_16x16x32_bf16 v[24:27], v[184:187], v[228:231], v[24:27]
	v_rcp_f32_e32 v126, v126
	v_mfma_f32_16x16x32_bf16 v[16:19], v[192:195], v[228:231], v[16:19]
	v_rcp_f32_e32 v127, v127
	v_mfma_f32_16x16x32_bf16 v[8:11], v[184:187], v[236:239], v[8:11]
	v_pk_mul_f32 v[114:115], v[118:119], v[114:115]
	v_mfma_f32_16x16x32_bf16 v[0:3], v[192:195], v[236:239], v[0:3]
	v_pk_mul_f32 v[112:113], v[116:117], v[112:113]
	v_mfma_f32_16x16x32_bf16 v[56:59], v[188:191], v[214:217], v[56:59]
	v_pk_mul_f32 v[116:117], v[150:151], v[124:125] op_sel_hi:[0,1]
	v_mfma_f32_16x16x32_bf16 v[48:51], v[196:199], v[214:217], v[48:51]
	v_pk_mul_f32 v[118:119], v[150:151], v[126:127] op_sel_hi:[0,1]
	v_mfma_f32_16x16x32_bf16 v[40:43], v[188:191], v[224:227], v[40:43]
	v_pk_mul_f32 v[114:115], v[114:115], v[116:117]
	v_mfma_f32_16x16x32_bf16 v[32:35], v[196:199], v[224:227], v[32:35]
	v_cvt_pk_bf16_f32 v116, v120, v121
	v_mfma_f32_16x16x32_bf16 v[24:27], v[188:191], v[232:235], v[24:27]
	v_cvt_pk_bf16_f32 v117, v122, v123
	v_mfma_f32_16x16x32_bf16 v[16:19], v[196:199], v[232:235], v[16:19]
	v_pk_mul_f32 v[112:113], v[112:113], v[118:119]
	v_mfma_f32_16x16x32_bf16 v[8:11], v[188:191], v[240:243], v[8:11]
	v_cvt_pk_bf16_f32 v118, v112, v113
	v_mfma_f32_16x16x32_bf16 v[0:3], v[196:199], v[240:243], v[0:3]
	v_cvt_pk_bf16_f32 v119, v114, v115
	s_setprio 0
	s_barrier
	s_branch .Lmy_up_lastj
.Lmy_up_lastn:
	s_barrier
	s_setprio 1
	s_waitcnt lgkmcnt(0)
	v_mfma_f32_16x16x32_bf16 v[60:63], v[138:141], v[210:213], v[60:63]
	v_mfma_f32_16x16x32_bf16 v[52:55], v[176:179], v[210:213], v[52:55]
	v_mfma_f32_16x16x32_bf16 v[44:47], v[138:141], v[218:221], v[44:47]
	v_mfma_f32_16x16x32_bf16 v[36:39], v[176:179], v[218:221], v[36:39]
	v_mfma_f32_16x16x32_bf16 v[28:31], v[138:141], v[228:231], v[28:31]
	v_mfma_f32_16x16x32_bf16 v[20:23], v[176:179], v[228:231], v[20:23]
	v_mfma_f32_16x16x32_bf16 v[12:15], v[138:141], v[236:239], v[12:15]
	v_mfma_f32_16x16x32_bf16 v[4:7], v[176:179], v[236:239], v[4:7]
	v_mfma_f32_16x16x32_bf16 v[60:63], v[172:175], v[214:217], v[60:63]
	v_mfma_f32_16x16x32_bf16 v[52:55], v[180:183], v[214:217], v[52:55]
	v_mfma_f32_16x16x32_bf16 v[44:47], v[172:175], v[224:227], v[44:47]
	v_mfma_f32_16x16x32_bf16 v[36:39], v[180:183], v[224:227], v[36:39]
	v_mfma_f32_16x16x32_bf16 v[28:31], v[172:175], v[232:235], v[28:31]
	v_mfma_f32_16x16x32_bf16 v[20:23], v[180:183], v[232:235], v[20:23]
	v_mfma_f32_16x16x32_bf16 v[12:15], v[172:175], v[240:243], v[12:15]
	v_mfma_f32_16x16x32_bf16 v[4:7], v[180:183], v[240:243], v[4:7]
	s_setprio 0
	s_setprio 1
	v_mfma_f32_16x16x32_bf16 v[56:59], v[184:187], v[210:213], v[56:59]
	v_mfma_f32_16x16x32_bf16 v[48:51], v[192:195], v[210:213], v[48:51]
	v_mfma_f32_16x16x32_bf16 v[40:43], v[184:187], v[218:221], v[40:43]
	v_mfma_f32_16x16x32_bf16 v[32:35], v[192:195], v[218:221], v[32:35]
	v_mfma_f32_16x16x32_bf16 v[24:27], v[184:187], v[228:231], v[24:27]
	v_mfma_f32_16x16x32_bf16 v[16:19], v[192:195], v[228:231], v[16:19]
	v_mfma_f32_16x16x32_bf16 v[8:11], v[184:187], v[236:239], v[8:11]
	v_mfma_f32_16x16x32_bf16 v[0:3], v[192:195], v[236:239], v[0:3]
	v_mfma_f32_16x16x32_bf16 v[56:59], v[188:191], v[214:217], v[56:59]
	v_mfma_f32_16x16x32_bf16 v[48:51], v[196:199], v[214:217], v[48:51]
	v_mfma_f32_16x16x32_bf16 v[40:43], v[188:191], v[224:227], v[40:43]
	v_mfma_f32_16x16x32_bf16 v[32:35], v[196:199], v[224:227], v[32:35]
	v_mfma_f32_16x16x32_bf16 v[24:27], v[188:191], v[232:235], v[24:27]
	v_mfma_f32_16x16x32_bf16 v[16:19], v[196:199], v[232:235], v[16:19]
	v_mfma_f32_16x16x32_bf16 v[8:11], v[188:191], v[240:243], v[8:11]
	v_mfma_f32_16x16x32_bf16 v[0:3], v[196:199], v[240:243], v[0:3]
	s_setprio 0
	s_barrier
.Lmy_up_lastj:
	s_add_i32 s85, s85, 2
	s_add_u32 s89, s89, 0x100
	s_addc_u32 s84, s84, 0
	s_add_u32 s60, s60, 0x100
	s_addc_u32 s61, s61, 0
	s_cmp_gt_u32 s85, 13
	s_cbranch_scc0 .LBB0_180
	s_and_b64 vcc, exec, s[18:19]
	s_cbranch_vccz .LBB0_183
	s_barrier
.LBB0_183:
	s_lshl_b32 s47, s81, 7
	s_and_b32 s47, s47, 0xc00
	v_add_u32_e32 v138, s47, v146
	ds_read2_b32 v[172:173], v138 offset1:16
	ds_read2_b32 v[142:143], v138 offset0:32 offset1:48
	ds_read2_b32 v[140:141], v138 offset0:128 offset1:144
	ds_read2_b32 v[138:139], v138 offset0:160 offset1:176
	s_waitcnt lgkmcnt(0)
	s_bitcmp1_b32 s18, 0
	s_cbranch_scc0 .Lmy_up_e1
	v_add_u32_e32 v244, 0x14000, v145
	ds_read_b128 v[184:187], v244
	ds_read_b128 v[188:191], v244 offset:1024
	ds_read_b128 v[192:195], v244 offset:2048
	ds_read_b128 v[196:199], v244 offset:3072
	v_add_u32_e32 v245, 0x10000, v145
	ds_read_b128 v[180:183], v245 offset:3072
	ds_read_b128 v[210:213], v148
	ds_read_b128 v[214:217], v148 offset:1024
	ds_read_b128 v[218:221], v148 offset:2048
	ds_read_b128 v[224:227], v148 offset:3072
	ds_read_b128 v[228:231], v148 offset:4096
	ds_read_b128 v[232:235], v148 offset:5120
	ds_read_b128 v[236:239], v148 offset:6144
	ds_read_b128 v[240:243], v148 offset:7168
.Lmy_up_e1:
	s_lshl_b32 s21, s81, 8
	s_add_i32 s21, s21, s76
	v_mul_f32_e32 v122, 0xbfb8aa3b, v173
	s_ashr_i32 s60, s21, 12
	v_pk_mul_f32 v[124:125], v[110:111], v[122:123] op_sel_hi:[1,0]
	v_pk_mul_f32 v[126:127], v[108:109], v[122:123] op_sel_hi:[1,0]
	v_or_b32_e32 v149, s21, v144
	v_lshl_or_b32 v150, s80, 7, v147
	s_ashr_i32 s61, s60, 31
	v_mov_b64_e32 v[112:113], s[56:57]
	v_exp_f32_e32 v126, v126
	v_exp_f32_e32 v124, v124
	v_exp_f32_e32 v125, v125
	v_exp_f32_e32 v127, v127
	v_ashrrev_i32_e32 v151, 31, v150
	v_mad_i64_i32 v[114:115], s[62:63], v149, s24, v[112:113]
	s_lshl_b64 s[60:61], s[60:61], 22
	v_lshl_add_u64 v[120:121], v[114:115], 0, s[60:61]
	v_lshlrev_b64 v[114:115], 1, v[150:151]
	v_lshl_add_u64 v[120:121], v[120:121], 0, v[114:115]
	global_store_dwordx4 v[120:121], v[116:119], off
	v_pk_add_f32 v[120:121], v[126:127], 1.0 op_sel_hi:[1,0]
	v_pk_mul_f32 v[106:107], v[110:111], v[106:107]
	v_pk_add_f32 v[118:119], v[124:125], 1.0 op_sel_hi:[1,0]
	v_rcp_f32_e32 v120, v120
	v_rcp_f32_e32 v118, v118
	v_rcp_f32_e32 v119, v119
	v_rcp_f32_e32 v121, v121
	v_mul_f32_e32 v116, v173, v173
	v_pk_mul_f32 v[104:105], v[108:109], v[104:105]
	v_pk_mul_f32 v[108:109], v[116:117], v[118:119] op_sel_hi:[0,1]
	v_pk_mul_f32 v[110:111], v[116:117], v[120:121] op_sel_hi:[0,1]
	v_pk_mul_f32 v[118:119], v[102:103], v[122:123] op_sel_hi:[1,0]
	v_pk_mul_f32 v[120:121], v[100:101], v[122:123] op_sel_hi:[1,0]
	v_exp_f32_e32 v118, v118
	v_exp_f32_e32 v120, v120
	v_exp_f32_e32 v119, v119
	v_exp_f32_e32 v121, v121
	v_pk_mul_f32 v[106:107], v[106:107], v[108:109]
	v_pk_mul_f32 v[104:105], v[104:105], v[110:111]
	v_pk_add_f32 v[108:109], v[118:119], 1.0 op_sel_hi:[1,0]
	v_pk_add_f32 v[110:111], v[120:121], 1.0 op_sel_hi:[1,0]
	v_rcp_f32_e32 v108, v108
	v_rcp_f32_e32 v110, v110
	v_rcp_f32_e32 v109, v109
	v_rcp_f32_e32 v111, v111
	v_pk_mul_f32 v[98:99], v[102:103], v[98:99]
	v_pk_mul_f32 v[96:97], v[100:101], v[96:97]
	v_pk_mul_f32 v[100:101], v[116:117], v[108:109] op_sel_hi:[0,1]
	v_pk_mul_f32 v[102:103], v[116:117], v[110:111] op_sel_hi:[0,1]
	v_pk_mul_f32 v[100:101], v[98:99], v[100:101]
	v_pk_mul_f32 v[98:99], v[96:97], v[102:103]
	v_or_b32_e32 v102, 16, v149
	v_cvt_pk_bf16_f32 v96, v104, v105
	v_cvt_pk_bf16_f32 v97, v106, v107
	v_cvt_pk_bf16_f32 v98, v98, v99
	v_cvt_pk_bf16_f32 v99, v100, v101
	v_mad_i64_i32 v[100:101], s[62:63], v102, s24, v[112:113]
	v_mul_f32_e32 v102, 0xbfb8aa3b, v142
	v_pk_mul_f32 v[104:105], v[94:95], v[102:103] op_sel_hi:[1,0]
	v_pk_mul_f32 v[106:107], v[92:93], v[102:103] op_sel_hi:[1,0]
	v_exp_f32_e32 v104, v104
	v_exp_f32_e32 v106, v106
	v_exp_f32_e32 v105, v105
	v_exp_f32_e32 v107, v107
	v_lshl_add_u64 v[100:101], v[100:101], 0, s[60:61]
	v_lshl_add_u64 v[100:101], v[100:101], 0, v[114:115]
	global_store_dwordx4 v[100:101], v[96:99], off
	v_pk_add_f32 v[100:101], v[106:107], 1.0 op_sel_hi:[1,0]
	v_pk_mul_f32 v[90:91], v[94:95], v[90:91]
	v_pk_add_f32 v[98:99], v[104:105], 1.0 op_sel_hi:[1,0]
	v_rcp_f32_e32 v100, v100
	v_rcp_f32_e32 v98, v98
	v_rcp_f32_e32 v99, v99
	v_rcp_f32_e32 v101, v101
	v_mul_f32_e32 v96, v142, v142
	v_pk_mul_f32 v[88:89], v[92:93], v[88:89]
	v_pk_mul_f32 v[92:93], v[96:97], v[98:99] op_sel_hi:[0,1]
	v_pk_mul_f32 v[94:95], v[96:97], v[100:101] op_sel_hi:[0,1]
	v_pk_mul_f32 v[98:99], v[86:87], v[102:103] op_sel_hi:[1,0]
	v_pk_mul_f32 v[100:101], v[84:85], v[102:103] op_sel_hi:[1,0]
	v_exp_f32_e32 v98, v98
	v_exp_f32_e32 v100, v100
	v_exp_f32_e32 v99, v99
	v_exp_f32_e32 v101, v101
	v_pk_mul_f32 v[90:91], v[90:91], v[92:93]
	v_pk_mul_f32 v[88:89], v[88:89], v[94:95]
	v_pk_add_f32 v[92:93], v[98:99], 1.0 op_sel_hi:[1,0]
	v_pk_add_f32 v[94:95], v[100:101], 1.0 op_sel_hi:[1,0]
	v_rcp_f32_e32 v92, v92
	v_rcp_f32_e32 v94, v94
	v_rcp_f32_e32 v93, v93
	v_rcp_f32_e32 v95, v95
	v_pk_mul_f32 v[82:83], v[86:87], v[82:83]
	v_pk_mul_f32 v[80:81], v[84:85], v[80:81]
	v_pk_mul_f32 v[84:85], v[96:97], v[92:93] op_sel_hi:[0,1]
	v_pk_mul_f32 v[86:87], v[96:97], v[94:95] op_sel_hi:[0,1]
	v_pk_mul_f32 v[84:85], v[82:83], v[84:85]
	v_pk_mul_f32 v[82:83], v[80:81], v[86:87]
	v_or_b32_e32 v86, 32, v149
	v_cvt_pk_bf16_f32 v80, v88, v89
	v_cvt_pk_bf16_f32 v81, v90, v91
	v_cvt_pk_bf16_f32 v82, v82, v83
	v_cvt_pk_bf16_f32 v83, v84, v85
	v_mad_i64_i32 v[84:85], s[62:63], v86, s24, v[112:113]
	v_mul_f32_e32 v86, 0xbfb8aa3b, v143
	v_pk_mul_f32 v[88:89], v[78:79], v[86:87] op_sel_hi:[1,0]
	v_pk_mul_f32 v[90:91], v[76:77], v[86:87] op_sel_hi:[1,0]
	v_exp_f32_e32 v88, v88
	v_exp_f32_e32 v90, v90
	v_exp_f32_e32 v89, v89
	v_exp_f32_e32 v91, v91
	v_lshl_add_u64 v[84:85], v[84:85], 0, s[60:61]
	v_lshl_add_u64 v[84:85], v[84:85], 0, v[114:115]
	global_store_dwordx4 v[84:85], v[80:83], off
	v_pk_add_f32 v[84:85], v[90:91], 1.0 op_sel_hi:[1,0]
	v_pk_mul_f32 v[74:75], v[78:79], v[74:75]
	v_pk_add_f32 v[82:83], v[88:89], 1.0 op_sel_hi:[1,0]
	v_rcp_f32_e32 v84, v84
	v_rcp_f32_e32 v82, v82
	v_rcp_f32_e32 v83, v83
	v_rcp_f32_e32 v85, v85
	v_mul_f32_e32 v80, v143, v143
	v_pk_mul_f32 v[72:73], v[76:77], v[72:73]
	v_pk_mul_f32 v[76:77], v[80:81], v[82:83] op_sel_hi:[0,1]
	v_pk_mul_f32 v[78:79], v[80:81], v[84:85] op_sel_hi:[0,1]
	v_pk_mul_f32 v[82:83], v[70:71], v[86:87] op_sel_hi:[1,0]
	v_pk_mul_f32 v[84:85], v[68:69], v[86:87] op_sel_hi:[1,0]
	v_exp_f32_e32 v82, v82
	v_exp_f32_e32 v84, v84
	v_exp_f32_e32 v83, v83
	v_exp_f32_e32 v85, v85
	v_pk_mul_f32 v[74:75], v[74:75], v[76:77]
	v_pk_mul_f32 v[72:73], v[72:73], v[78:79]
	v_pk_add_f32 v[76:77], v[82:83], 1.0 op_sel_hi:[1,0]
	v_pk_add_f32 v[78:79], v[84:85], 1.0 op_sel_hi:[1,0]
	v_rcp_f32_e32 v76, v76
	v_rcp_f32_e32 v78, v78
	v_rcp_f32_e32 v77, v77
	v_rcp_f32_e32 v79, v79
	v_pk_mul_f32 v[66:67], v[70:71], v[66:67]
	v_pk_mul_f32 v[64:65], v[68:69], v[64:65]
	v_pk_mul_f32 v[68:69], v[80:81], v[76:77] op_sel_hi:[0,1]
	v_pk_mul_f32 v[70:71], v[80:81], v[78:79] op_sel_hi:[0,1]
	v_pk_mul_f32 v[68:69], v[66:67], v[68:69]
	v_pk_mul_f32 v[66:67], v[64:65], v[70:71]
	v_or_b32_e32 v70, 48, v149
	v_cvt_pk_bf16_f32 v64, v72, v73
	v_cvt_pk_bf16_f32 v65, v74, v75
	v_cvt_pk_bf16_f32 v66, v66, v67
	v_cvt_pk_bf16_f32 v67, v68, v69
	v_mad_i64_i32 v[68:69], s[62:63], v70, s24, v[112:113]
	v_lshl_add_u64 v[68:69], v[68:69], 0, s[60:61]
	v_lshl_add_u64 v[68:69], v[68:69], 0, v[114:115]
	global_store_dwordx4 v[68:69], v[64:67], off
	v_add_u32_e32 v73, 0x80, v149
	v_mul_f32_e32 v72, v140, v140
	v_mul_f32_e32 v66, 0xbfb8aa3b, v140
	v_pk_mul_f32 v[68:69], v[62:63], v[66:67] op_sel_hi:[1,0]
	v_pk_mul_f32 v[70:71], v[60:61], v[66:67] op_sel_hi:[1,0]
	v_exp_f32_e32 v68, v68
	v_exp_f32_e32 v69, v69
	v_exp_f32_e32 v70, v70
	v_exp_f32_e32 v71, v71
	v_pk_mul_f32 v[56:57], v[60:61], v[56:57]
	v_pk_add_f32 v[68:69], v[68:69], 1.0 op_sel_hi:[1,0]
	v_pk_mul_f32 v[58:59], v[62:63], v[58:59]
	v_rcp_f32_e32 v68, v68
	v_rcp_f32_e32 v69, v69
	v_pk_add_f32 v[70:71], v[70:71], 1.0 op_sel_hi:[1,0]
	v_pk_mul_f32 v[50:51], v[54:55], v[50:51]
	v_rcp_f32_e32 v70, v70
	v_pk_mul_f32 v[60:61], v[72:73], v[68:69] op_sel_hi:[0,1]
	v_pk_mul_f32 v[68:69], v[54:55], v[66:67] op_sel_hi:[1,0]
	v_rcp_f32_e32 v71, v71
	v_pk_mul_f32 v[66:67], v[52:53], v[66:67] op_sel_hi:[1,0]
	v_exp_f32_e32 v68, v68
	v_exp_f32_e32 v69, v69
	v_exp_f32_e32 v66, v66
	v_exp_f32_e32 v67, v67
	v_pk_mul_f32 v[62:63], v[72:73], v[70:71] op_sel_hi:[0,1]
	v_pk_mul_f32 v[58:59], v[58:59], v[60:61]
	v_pk_add_f32 v[60:61], v[68:69], 1.0 op_sel_hi:[1,0]
	v_pk_mul_f32 v[56:57], v[56:57], v[62:63]
	v_pk_add_f32 v[62:63], v[66:67], 1.0 op_sel_hi:[1,0]
	v_rcp_f32_e32 v60, v60
	v_rcp_f32_e32 v61, v61
	v_rcp_f32_e32 v62, v62
	v_rcp_f32_e32 v63, v63
	v_pk_mul_f32 v[48:49], v[52:53], v[48:49]
	v_pk_mul_f32 v[52:53], v[72:73], v[60:61] op_sel_hi:[0,1]
	v_pk_mul_f32 v[60:61], v[50:51], v[52:53]
	v_pk_mul_f32 v[54:55], v[72:73], v[62:63] op_sel_hi:[0,1]
	v_cvt_pk_bf16_f32 v50, v56, v57
	v_mul_f32_e32 v56, 0xbfb8aa3b, v141
	v_ashrrev_i32_e32 v64, 12, v73
	v_pk_mul_f32 v[48:49], v[48:49], v[54:55]
	v_cvt_pk_bf16_f32 v51, v58, v59
	v_pk_mul_f32 v[58:59], v[46:47], v[56:57] op_sel_hi:[1,0]
	v_cvt_pk_bf16_f32 v52, v48, v49
	v_cvt_pk_bf16_f32 v53, v60, v61
	v_pk_mul_f32 v[60:61], v[44:45], v[56:57] op_sel_hi:[1,0]
	v_ashrrev_i32_e32 v65, 31, v64
	v_exp_f32_e32 v60, v60
	v_exp_f32_e32 v58, v58
	v_exp_f32_e32 v59, v59
	v_exp_f32_e32 v61, v61
	v_mad_i64_i32 v[54:55], s[60:61], v73, s24, v[112:113]
	v_lshlrev_b64 v[48:49], 22, v[64:65]
	v_lshl_add_u64 v[54:55], v[54:55], 0, v[48:49]
	v_lshl_add_u64 v[54:55], v[54:55], 0, v[114:115]
	global_store_dwordx4 v[54:55], v[50:53], off
	v_pk_add_f32 v[54:55], v[60:61], 1.0 op_sel_hi:[1,0]
	v_pk_mul_f32 v[42:43], v[46:47], v[42:43]
	v_pk_add_f32 v[52:53], v[58:59], 1.0 op_sel_hi:[1,0]
	v_rcp_f32_e32 v54, v54
	v_rcp_f32_e32 v52, v52
	v_rcp_f32_e32 v53, v53
	v_rcp_f32_e32 v55, v55
	v_mul_f32_e32 v50, v141, v141
	v_pk_mul_f32 v[40:41], v[44:45], v[40:41]
	v_pk_mul_f32 v[44:45], v[50:51], v[52:53] op_sel_hi:[0,1]
	v_pk_mul_f32 v[46:47], v[50:51], v[54:55] op_sel_hi:[0,1]
	v_pk_mul_f32 v[52:53], v[38:39], v[56:57] op_sel_hi:[1,0]
	v_pk_mul_f32 v[54:55], v[36:37], v[56:57] op_sel_hi:[1,0]
	v_exp_f32_e32 v52, v52
	v_exp_f32_e32 v54, v54
	v_exp_f32_e32 v53, v53
	v_exp_f32_e32 v55, v55
	v_pk_mul_f32 v[42:43], v[42:43], v[44:45]
	v_pk_mul_f32 v[40:41], v[40:41], v[46:47]
	v_pk_add_f32 v[44:45], v[52:53], 1.0 op_sel_hi:[1,0]
	v_pk_add_f32 v[46:47], v[54:55], 1.0 op_sel_hi:[1,0]
	v_rcp_f32_e32 v44, v44
	v_rcp_f32_e32 v46, v46
	v_rcp_f32_e32 v45, v45
	v_rcp_f32_e32 v47, v47
	v_pk_mul_f32 v[34:35], v[38:39], v[34:35]
	v_pk_mul_f32 v[32:33], v[36:37], v[32:33]
	v_pk_mul_f32 v[36:37], v[50:51], v[44:45] op_sel_hi:[0,1]
	v_pk_mul_f32 v[38:39], v[50:51], v[46:47] op_sel_hi:[0,1]
	v_pk_mul_f32 v[36:37], v[34:35], v[36:37]
	v_pk_mul_f32 v[34:35], v[32:33], v[38:39]
	v_add_u32_e32 v38, 0x90, v149
	v_cvt_pk_bf16_f32 v32, v40, v41
	v_cvt_pk_bf16_f32 v33, v42, v43
	v_cvt_pk_bf16_f32 v34, v34, v35
	v_cvt_pk_bf16_f32 v35, v36, v37
	v_mad_i64_i32 v[36:37], s[60:61], v38, s24, v[112:113]
	v_mul_f32_e32 v38, 0xbfb8aa3b, v138
	v_pk_mul_f32 v[40:41], v[30:31], v[38:39] op_sel_hi:[1,0]
	v_pk_mul_f32 v[42:43], v[28:29], v[38:39] op_sel_hi:[1,0]
	v_exp_f32_e32 v40, v40
	v_exp_f32_e32 v42, v42
	v_exp_f32_e32 v41, v41
	v_exp_f32_e32 v43, v43
	v_lshl_add_u64 v[36:37], v[36:37], 0, v[48:49]
	v_lshl_add_u64 v[36:37], v[36:37], 0, v[114:115]
	global_store_dwordx4 v[36:37], v[32:35], off
	v_pk_add_f32 v[36:37], v[42:43], 1.0 op_sel_hi:[1,0]
	v_pk_mul_f32 v[26:27], v[30:31], v[26:27]
	v_pk_add_f32 v[34:35], v[40:41], 1.0 op_sel_hi:[1,0]
	v_rcp_f32_e32 v36, v36
	v_rcp_f32_e32 v34, v34
	v_rcp_f32_e32 v35, v35
	v_rcp_f32_e32 v37, v37
	v_mul_f32_e32 v32, v138, v138
	v_pk_mul_f32 v[24:25], v[28:29], v[24:25]
	v_pk_mul_f32 v[28:29], v[32:33], v[34:35] op_sel_hi:[0,1]
	v_pk_mul_f32 v[30:31], v[32:33], v[36:37] op_sel_hi:[0,1]
	v_pk_mul_f32 v[34:35], v[22:23], v[38:39] op_sel_hi:[1,0]
	v_pk_mul_f32 v[36:37], v[20:21], v[38:39] op_sel_hi:[1,0]
	v_exp_f32_e32 v34, v34
	v_exp_f32_e32 v36, v36
	v_exp_f32_e32 v35, v35
	v_exp_f32_e32 v37, v37
	v_pk_mul_f32 v[26:27], v[26:27], v[28:29]
	v_pk_mul_f32 v[24:25], v[24:25], v[30:31]
	v_pk_add_f32 v[28:29], v[34:35], 1.0 op_sel_hi:[1,0]
	v_pk_add_f32 v[30:31], v[36:37], 1.0 op_sel_hi:[1,0]
	v_rcp_f32_e32 v28, v28
	v_rcp_f32_e32 v30, v30
	v_rcp_f32_e32 v29, v29
	v_rcp_f32_e32 v31, v31
	v_pk_mul_f32 v[18:19], v[22:23], v[18:19]
	v_pk_mul_f32 v[16:17], v[20:21], v[16:17]
	v_pk_mul_f32 v[20:21], v[32:33], v[28:29] op_sel_hi:[0,1]
	v_pk_mul_f32 v[22:23], v[32:33], v[30:31] op_sel_hi:[0,1]
	v_pk_mul_f32 v[20:21], v[18:19], v[20:21]
	v_pk_mul_f32 v[18:19], v[16:17], v[22:23]
	v_add_u32_e32 v22, 0xa0, v149
	v_cvt_pk_bf16_f32 v16, v24, v25
	v_cvt_pk_bf16_f32 v17, v26, v27
	v_cvt_pk_bf16_f32 v18, v18, v19
	v_cvt_pk_bf16_f32 v19, v20, v21
	v_mad_i64_i32 v[20:21], s[60:61], v22, s24, v[112:113]
	v_lshl_add_u64 v[20:21], v[20:21], 0, v[48:49]
	v_lshl_add_u64 v[20:21], v[20:21], 0, v[114:115]
	global_store_dwordx4 v[20:21], v[16:19], off
	v_add_u32_e32 v22, 0xb0, v149
	v_mad_i64_i32 v[28:29], s[60:61], v22, s24, v[112:113]
	v_lshl_add_u64 v[28:29], v[28:29], 0, v[48:49]
	v_lshl_add_u64 v[28:29], v[28:29], 0, v[114:115]
	v_mov_b32_e32 v30, v139
	s_andn2_b64 vcc, exec, s[44:45]
	s_mov_b64 s[44:45], -1
	s_cbranch_vccnz .Lmy_up_g7_inline
	s_andn2_b64 vcc, exec, s[16:17]
	s_cbranch_vccnz .LBB0_175
	s_barrier
	s_branch .LBB0_175
